# resid gemm80 loop: SGPR-addressed LDS-DMA issue (no VALU/readfirstlane in the DMA block)
# speedup vs baseline: 1.0341x; 1.0012x over previous
.LBB0_261:
	s_ashr_i32 s26, s70, 31
	s_lshr_b32 s26, s26, 26
	s_add_i32 s26, s70, s26
	s_and_b32 s28, s26, 0xfffffc0
	s_sub_i32 s28, s70, s28
	s_mul_i32 s54, s28, 0x50
	s_ashr_i32 s55, s54, 31
	v_mov_b32_e32 v1, v208
	s_lshl_b64 s[38:39], s[54:55], s64
	s_lshl_b64 s[38:39], s[38:39], 1
	v_ashrrev_i32_e32 v0, 6, v1
	v_bfe_u32 v4, v1, 3, 3
	v_lshl_or_b32 v4, v0, 3, v4
	s_add_u32 s38, s24, s38
	v_lshrrev_b32_e32 v2, 3, v1
	v_ashrrev_i32_e32 v5, 31, v4
	s_addc_u32 s39, s25, s39
	v_writelane_b32 v255, s60, 61
	v_writelane_b32 v255, s61, 62
	s_mov_b64 s[60:61], s[38:39]
	v_bitop3_b32 v3, v2, v1, 7 bitop3:0x28
	v_lshlrev_b64 v[4:5], s64, v[4:5]
	v_lshl_add_u64 v[4:5], v[4:5], 1, s[38:39]
	v_lshlrev_b32_e32 v128, 4, v3
	v_lshlrev_b32_e32 v42, 10, v0
	v_lshl_add_u64 v[40:41], v[4:5], 0, v[128:129]
	v_readfirstlane_b32 s28, v42
	v_readfirstlane_b32 s55, v42
	v_subrev_u32_e32 v134, s60, v40
	v_add_u32_e32 v4, 0x1000, v42
	s_waitcnt lgkmcnt(0)
	s_barrier
	s_mov_b32 m0, s28
	v_readfirstlane_b32 s28, v4
	global_load_lds_dwordx4 v[40:41], off
	v_lshl_add_u64 v[44:45], v[40:41], 0, s[44:45]
	s_mov_b32 m0, s28
	v_cmp_gt_i32_e64 s[38:39], 2, v0
	global_load_lds_dwordx4 v[44:45], off
	v_lshl_add_u64 v[46:47], v[44:45], 0, s[44:45]
	s_and_saveexec_b64 s[40:41], s[38:39]
	s_cbranch_execz .LBB0_263
	v_add_u32_e32 v4, 0x2000, v42
	s_nop 0
	v_readfirstlane_b32 s28, v4
	s_mov_b32 m0, s28
	s_nop 0
	global_load_lds_dwordx4 v[46:47], off
.LBB0_263:
	s_or_b64 exec, exec, s[40:41]
	s_ashr_i32 s40, s26, 6
	s_ashr_i32 s41, s40, 31
	s_lshl_b64 s[56:57], s[40:41], 7
	v_lshrrev_b32_e32 v5, 2, v1
	v_lshlrev_b32_e32 v4, 3, v3
	s_lshl_b64 s[56:57], s[56:57], s64
	v_lshlrev_b32_e32 v3, 5, v0
	v_and_b32_e32 v5, 8, v5
	v_and_b32_e32 v2, 3, v2
	s_lshl_b64 s[56:57], s[56:57], 1
	v_or3_b32 v2, v3, v5, v2
	s_add_u32 s56, s62, s56
	v_ashrrev_i32_e32 v3, 31, v2
	s_addc_u32 s57, s63, s57
	s_mov_b64 s[58:59], s[56:57]
	v_lshlrev_b64 v[2:3], s64, v[2:3]
	v_lshl_add_u64 v[2:3], v[2:3], 1, s[56:57]
	v_lshlrev_b32_e32 v128, 1, v4
	v_lshl_add_u64 v[48:49], v[2:3], 0, v[128:129]
	v_subrev_u32_e32 v135, s58, v48
	v_mad_u64_u32 v[2:3], s[56:57], v0, s84, v[42:43]
	v_add_u32_e32 v3, 0x4000, v2
	v_lshl_add_u64 v[50:51], v[48:49], 0, s[46:47]
	v_readfirstlane_b32 s26, v3
	v_add_u32_e32 v3, 0x4400, v2
	s_mov_b32 m0, s26
	v_readfirstlane_b32 s26, v3
	v_add_u32_e32 v3, 0x4800, v2
	global_load_lds_dwordx4 v[48:49], off
	s_mov_b32 m0, s26
	v_readfirstlane_b32 s26, v3
	v_add_u32_e32 v2, 0x4c00, v2
	global_load_lds_dwordx4 v[50:51], off
	v_lshl_add_u64 v[52:53], v[50:51], 0, s[52:53]
	s_mov_b32 m0, s26
	v_readfirstlane_b32 s26, v2
	global_load_lds_dwordx4 v[52:53], off
	v_lshl_add_u64 v[54:55], v[48:49], 0, s[48:49]
	s_mov_b32 m0, s26
	v_and_b32_e32 v2, 7, v1
	global_load_lds_dwordx4 v[54:55], off
	v_lshlrev_b32_e32 v3, 7, v1
	v_lshlrev_b32_e32 v2, 4, v2
	v_and_b32_e32 v3, 0x780, v3
	v_bitop3_b32 v1, v2, v1, 48 bitop3:0x78
	v_lshlrev_b32_e32 v57, 12, v0
	v_mov_b32_e32 v4, 0
	v_or_b32_e32 v43, v1, v3
	s_mov_b32 s28, 64
	v_bitop3_b32 v56, v1, 64, v3 bitop3:0x36
	v_add_u32_e32 v58, 0x4000, v57
	s_mov_b32 s41, 0
	s_mov_b32 s26, 0
	v_mov_b32_e32 v5, v4
	v_mov_b32_e32 v6, v4
	v_mov_b32_e32 v7, v4
	v_mov_b32_e32 v0, v4
	v_mov_b32_e32 v1, v4
	v_mov_b32_e32 v2, v4
	v_mov_b32_e32 v3, v4
	v_mov_b32_e32 v8, v4
	v_mov_b32_e32 v9, v4
	v_mov_b32_e32 v10, v4
	v_mov_b32_e32 v11, v4
	v_mov_b32_e32 v12, v4
	v_mov_b32_e32 v13, v4
	v_mov_b32_e32 v14, v4
	v_mov_b32_e32 v15, v4
	v_mov_b32_e32 v16, v4
	v_mov_b32_e32 v17, v4
	v_mov_b32_e32 v18, v4
	v_mov_b32_e32 v19, v4
	v_mov_b32_e32 v20, v4
	v_mov_b32_e32 v21, v4
	v_mov_b32_e32 v22, v4
	v_mov_b32_e32 v23, v4
	v_mov_b32_e32 v24, v4
	v_mov_b32_e32 v25, v4
	v_mov_b32_e32 v26, v4
	v_mov_b32_e32 v27, v4
	v_mov_b32_e32 v28, v4
	v_mov_b32_e32 v29, v4
	v_mov_b32_e32 v30, v4
	v_mov_b32_e32 v31, v4
	v_mov_b32_e32 v32, v4
	v_mov_b32_e32 v33, v4
	v_mov_b32_e32 v34, v4
	v_mov_b32_e32 v35, v4
	v_mov_b32_e32 v36, v4
	v_mov_b32_e32 v37, v4
	v_mov_b32_e32 v38, v4
	v_mov_b32_e32 v39, v4
	s_cmp_gt_u32 s65, 1
	s_cbranch_scc0 .Lr80_p1
	s_lshl_b32 s71, s55, 2
	s_add_u32 s60, s60, 0x80
	s_addc_u32 s61, s61, 0
	s_add_u32 s58, s58, 0x80
	s_addc_u32 s59, s59, 0
	s_add_u32 s56, s55, 0x8000
	s_mov_b32 m0, s56
	s_add_u32 s72, s60, s44
	s_addc_u32 s73, s61, s45
	global_load_lds_dwordx4 v134, s[60:61]
	s_add_u32 m0, s56, 0x1000
	s_cmp_lg_u64 s[38:39], 0
	global_load_lds_dwordx4 v134, s[72:73]
	s_cbranch_scc0 .Lr80p_noA3
	s_add_u32 s72, s72, s44
	s_addc_u32 s73, s73, s45
	s_add_u32 m0, s56, 0x2000
	s_nop 0
	global_load_lds_dwordx4 v134, s[72:73]
.Lr80p_noA3:
	s_add_u32 s56, s71, 0x8000
	s_add_u32 m0, s56, 0x4000
	s_add_u32 s72, s58, s46
	s_addc_u32 s73, s59, s47
	global_load_lds_dwordx4 v135, s[58:59]
	s_add_u32 m0, s56, 0x4400
	s_nop 0
	global_load_lds_dwordx4 v135, s[72:73]
	s_add_u32 s72, s72, s52
	s_addc_u32 s73, s73, s53
	s_add_u32 m0, s56, 0x4800
	s_nop 0
	global_load_lds_dwordx4 v135, s[72:73]
	s_add_u32 s72, s58, s48
	s_addc_u32 s73, s59, s49
	s_add_u32 m0, s56, 0x4c00
	s_nop 0
	global_load_lds_dwordx4 v135, s[72:73]
	s_add_u32 s60, s60, 0x80
	s_addc_u32 s61, s61, 0
	s_add_u32 s58, s58, 0x80
	s_addc_u32 s59, s59, 0

.LBB0_266:
	s_add_i32 s56, s26, 1
	s_cmp_lt_u32 s56, s65
	s_cbranch_scc1 .Lr80_cnt
	s_waitcnt vmcnt(0)
	s_branch .Lr80_wd

.Lr80_wd:
	s_waitcnt lgkmcnt(0)
	s_barrier
	v_add_u32_e32 v60, s41, v58
	v_or_b32_e32 v59, s41, v43
	v_or_b32_e32 v116, s41, v56
	v_add_u32_e32 v117, v60, v43
	v_add_u32_e32 v118, v60, v56
	ds_read_b128 v[60:63], v59
	ds_read_b128 v[64:67], v59 offset:2048
	ds_read_b128 v[68:71], v59 offset:4096
	ds_read_b128 v[72:75], v59 offset:6144
	ds_read_b128 v[76:79], v59 offset:8192
	ds_read_b128 v[80:83], v117
	ds_read_b128 v[84:87], v117 offset:2048
	ds_read_b128 v[88:91], v116
	ds_read_b128 v[92:95], v116 offset:2048
	ds_read_b128 v[96:99], v116 offset:4096
	ds_read_b128 v[100:103], v116 offset:6144
	ds_read_b128 v[104:107], v116 offset:8192
	ds_read_b128 v[108:111], v118
	ds_read_b128 v[112:115], v118 offset:2048
	s_waitcnt lgkmcnt(7)
	v_mfma_f32_16x16x32_bf16 v[36:39], v[80:83], v[60:63], v[36:39]
	v_mfma_f32_16x16x32_bf16 v[32:35], v[84:87], v[60:63], v[32:35]
	v_mfma_f32_16x16x32_bf16 v[28:31], v[80:83], v[64:67], v[28:31]
	v_mfma_f32_16x16x32_bf16 v[24:27], v[84:87], v[64:67], v[24:27]
	v_mfma_f32_16x16x32_bf16 v[20:23], v[80:83], v[68:71], v[20:23]
	v_mfma_f32_16x16x32_bf16 v[16:19], v[84:87], v[68:71], v[16:19]
	v_mfma_f32_16x16x32_bf16 v[12:15], v[80:83], v[72:75], v[12:15]
	v_mfma_f32_16x16x32_bf16 v[0:3], v[80:83], v[76:79], v[0:3]
	v_mfma_f32_16x16x32_bf16 v[4:7], v[84:87], v[76:79], v[4:7]
	v_mfma_f32_16x16x32_bf16 v[8:11], v[84:87], v[72:75], v[8:11]
	s_waitcnt lgkmcnt(0)
	s_barrier
	s_add_i32 s56, s26, 2
	s_cmp_lt_u32 s56, s65
	s_cbranch_scc0 .Lr80_nd
	s_add_u32 s56, s55, s41
	s_mov_b32 m0, s56
	s_add_u32 s72, s60, s44
	s_addc_u32 s73, s61, s45
	global_load_lds_dwordx4 v134, s[60:61]
	s_add_u32 m0, s56, 0x1000
	s_cmp_lg_u64 s[38:39], 0
	global_load_lds_dwordx4 v134, s[72:73]
	s_cbranch_scc0 .Lr80i_noA3
	s_add_u32 s72, s72, s44
	s_addc_u32 s73, s73, s45
	s_add_u32 m0, s56, 0x2000
	s_nop 0
	global_load_lds_dwordx4 v134, s[72:73]
.Lr80i_noA3:
	s_add_u32 s56, s71, s41
	s_add_u32 m0, s56, 0x4000
	s_add_u32 s72, s58, s46
	s_addc_u32 s73, s59, s47
	global_load_lds_dwordx4 v135, s[58:59]
	s_add_u32 m0, s56, 0x4400
	s_nop 0
	global_load_lds_dwordx4 v135, s[72:73]
	s_add_u32 s72, s72, s52
	s_addc_u32 s73, s73, s53
	s_add_u32 m0, s56, 0x4800
	s_nop 0
	global_load_lds_dwordx4 v135, s[72:73]
	s_add_u32 s72, s58, s48
	s_addc_u32 s73, s59, s49
	s_add_u32 m0, s56, 0x4c00
	s_nop 0
	global_load_lds_dwordx4 v135, s[72:73]
	s_add_u32 s60, s60, 0x80
	s_addc_u32 s61, s61, 0
	s_add_u32 s58, s58, 0x80
	s_addc_u32 s59, s59, 0
.Lr80_nd:
	s_nop 0
	v_mfma_f32_16x16x32_bf16 v[36:39], v[108:111], v[88:91], v[36:39]
	v_mfma_f32_16x16x32_bf16 v[32:35], v[112:115], v[88:91], v[32:35]
	v_mfma_f32_16x16x32_bf16 v[28:31], v[108:111], v[92:95], v[28:31]
	v_mfma_f32_16x16x32_bf16 v[24:27], v[112:115], v[92:95], v[24:27]
	v_mfma_f32_16x16x32_bf16 v[20:23], v[108:111], v[96:99], v[20:23]
	v_mfma_f32_16x16x32_bf16 v[16:19], v[112:115], v[96:99], v[16:19]
	v_mfma_f32_16x16x32_bf16 v[12:15], v[108:111], v[100:103], v[12:15]
	v_mfma_f32_16x16x32_bf16 v[8:11], v[112:115], v[100:103], v[8:11]
	v_mfma_f32_16x16x32_bf16 v[0:3], v[108:111], v[104:107], v[0:3]
	v_mfma_f32_16x16x32_bf16 v[4:7], v[112:115], v[104:107], v[4:7]
	s_add_i32 s26, s26, 1
	s_add_i32 s28, s28, 64
	s_xor_b32 s41, s41, 0x8000
	s_cmp_lg_u32 s26, s65
	s_cbranch_scc1 .LBB0_266
	v_readlane_b32 s60, v255, 61
	v_readlane_b32 s61, v255, 62
